# w_out skinny split-K loops: loads issued up front, line halves adjacent (same edit as FFN-out skinny)
# speedup vs baseline: 1.0036x; 1.0036x over previous
; #define SK_MMA(A_, B_) do { _Pragma("unroll") for (int kk = 0; kk < 2; ++kk) _Pragma("unroll") for (int bj = 0; bj < 2; ++bj) _Pragma("unroll") for (int m = 0; m < 4; ++m) _Pragma("unroll") for (int n = 0; n < 2; ++n) \
;         acc[AI][bj][m][n] = __builtin_amdgcn_mfma_f32_16x16x32_bf16(B_[kk][bj][n], A_[kk][m], acc[AI][bj][m][n], 0, 0, 0); } while (0)
; template <class Epi, int AI>
; __device__ __forceinline__ void skinny_item(LAS unsigned char* lds, const Gemm g, const Epi& E, const Unit u, int wr, int wc, int wave, int lane) {
;     ...
;     const int nch = g.K >> 7, kbeg = ((wave * nch) >> 3) << 7, kend = (((wave + 1) * nch) >> 3) << 7;
;     bf16x8 a0[2][4], b0[2][2][2], a1[2][4], b1[2][2][2];
;     ...
; #pragma unroll 1
;     for (int k = kbeg; k < kend; k += 128) {
;         SK_LOAD(a0, b0, k);
;         SK_LOAD(a1, b1, k + 64);
;         SK_MMA(a0, b0);
;         SK_MMA(a1, b1);
;     }
.LBB0_1411:
	v_lshl_add_u64 v[104:105], v[92:93], 0, s[8:9]
	v_add_co_u32_e32 v186, vcc, s51, v104
	v_lshl_add_u64 v[106:107], v[66:67], 0, s[8:9]
	s_nop 1
	v_addc_co_u32_e32 v187, vcc, 0, v105, vcc
	v_lshl_add_u64 v[180:181], v[90:91], 0, s[8:9]
	v_add_co_u32_e32 v188, vcc, s51, v106
	v_lshl_add_u64 v[130:131], v[94:95], 0, s[8:9]
	v_lshl_add_u64 v[182:183], v[68:69], 0, s[8:9]
	v_lshl_add_u64 v[184:185], v[88:89], 0, s[8:9]
	v_addc_co_u32_e32 v189, vcc, 0, v107, vcc
	v_lshl_add_u64 v[164:165], v[70:71], 0, s[8:9]
	v_add_co_u32_e32 v190, vcc, s51, v164
	v_lshl_add_u64 v[168:169], v[64:65], 0, s[8:9]
	s_nop 1
	v_addc_co_u32_e32 v191, vcc, 0, v165, vcc
	v_add_co_u32_e32 v192, vcc, s51, v168
	s_nop 1
	v_addc_co_u32_e32 v193, vcc, 0, v169, vcc
	s_addk_i32 s20, 0x80
	s_add_u32 s8, s8, 0x100
	s_addc_u32 s9, s9, 0
	s_cmp_lt_i32 s20, s36
	global_load_dwordx4 v[104:107], v[130:131], off
	global_load_dwordx4 v[164:167], v[130:131], off offset:64
	global_load_dwordx4 v[168:171], v[186:187], off
	global_load_dwordx4 v[96:99], v[186:187], off offset:64
	global_load_dwordx4 v[100:103], v[180:181], off
	global_load_dwordx4 v[136:139], v[180:181], off offset:64
	global_load_dwordx4 v[140:143], v[182:183], off
	global_load_dwordx4 v[144:147], v[182:183], off offset:64
	global_load_dwordx4 v[148:151], v[184:185], off
	global_load_dwordx4 v[152:155], v[184:185], off offset:64
	global_load_dwordx4 v[156:159], v[188:189], off
	global_load_dwordx4 v[160:163], v[188:189], off offset:64
	global_load_dwordx4 v[172:175], v[190:191], off
	global_load_dwordx4 v[176:179], v[190:191], off offset:64
	global_load_dwordx4 v[194:197], v[192:193], off
	global_load_dwordx4 v[198:201], v[192:193], off offset:64
	global_load_dwordx4 v[202:205], v[130:131], off offset:128
	global_load_dwordx4 v[206:209], v[130:131], off offset:192
	global_load_dwordx4 v[210:213], v[186:187], off offset:128
	global_load_dwordx4 v[214:217], v[186:187], off offset:192
	global_load_dwordx4 v[218:221], v[180:181], off offset:128
	global_load_dwordx4 v[222:225], v[180:181], off offset:192
	global_load_dwordx4 v[226:229], v[182:183], off offset:128
	global_load_dwordx4 v[230:233], v[182:183], off offset:192
	global_load_dwordx4 v[234:237], v[184:185], off offset:128
	global_load_dwordx4 v[240:243], v[184:185], off offset:192
	global_load_dwordx4 v[244:247], v[188:189], off offset:128
	global_load_dwordx4 v[248:251], v[188:189], off offset:192
	s_waitcnt vmcnt(25)
	v_mfma_f32_16x16x32_bf16 v[56:59], v[168:171], v[104:107], v[56:59]
	s_waitcnt vmcnt(23)
	v_mfma_f32_16x16x32_bf16 v[52:55], v[168:171], v[100:103], v[52:55]
	s_waitcnt vmcnt(21)
	v_mfma_f32_16x16x32_bf16 v[44:47], v[168:171], v[140:143], v[44:47]
	s_waitcnt vmcnt(19)
	v_mfma_f32_16x16x32_bf16 v[36:39], v[168:171], v[148:151], v[36:39]
	s_waitcnt vmcnt(17)
	v_mfma_f32_16x16x32_bf16 v[60:63], v[156:159], v[104:107], v[60:63]
	v_mfma_f32_16x16x32_bf16 v[48:51], v[156:159], v[100:103], v[48:51]
	v_mfma_f32_16x16x32_bf16 v[40:43], v[156:159], v[140:143], v[40:43]
	v_mfma_f32_16x16x32_bf16 v[32:35], v[156:159], v[148:151], v[32:35]
	global_load_dwordx4 v[156:159], v[190:191], off offset:128
	s_waitcnt vmcnt(16)
	v_mfma_f32_16x16x32_bf16 v[28:31], v[172:175], v[104:107], v[28:31]
	v_mfma_f32_16x16x32_bf16 v[16:19], v[172:175], v[100:103], v[16:19]
	v_mfma_f32_16x16x32_bf16 v[4:7], v[172:175], v[140:143], v[4:7]
	v_mfma_f32_16x16x32_bf16 v[0:3], v[172:175], v[148:151], v[0:3]
	global_load_dwordx4 v[172:175], v[190:191], off offset:192
	v_mfma_f32_16x16x32_bf16 v[56:59], v[96:99], v[164:167], v[56:59]
	v_mfma_f32_16x16x32_bf16 v[60:63], v[160:163], v[164:167], v[60:63]
	v_mfma_f32_16x16x32_bf16 v[52:55], v[96:99], v[136:139], v[52:55]
	v_mfma_f32_16x16x32_bf16 v[48:51], v[160:163], v[136:139], v[48:51]
	v_mfma_f32_16x16x32_bf16 v[44:47], v[96:99], v[144:147], v[44:47]
	v_mfma_f32_16x16x32_bf16 v[40:43], v[160:163], v[144:147], v[40:43]
	v_mfma_f32_16x16x32_bf16 v[36:39], v[96:99], v[152:155], v[36:39]
	global_load_dwordx4 v[96:99], v[192:193], off offset:128
	s_waitcnt vmcnt(16)
; #define SK_MMA(A_, B_) do { _Pragma("unroll") for (int kk = 0; kk < 2; ++kk) _Pragma("unroll") for (int bj = 0; bj < 2; ++bj) _Pragma("unroll") for (int m = 0; m < 4; ++m) _Pragma("unroll") for (int n = 0; n < 2; ++n) \
;         acc[AI][bj][m][n] = __builtin_amdgcn_mfma_f32_16x16x32_bf16(B_[kk][bj][n], A_[kk][m], acc[AI][bj][m][n], 0, 0, 0); } while (0)
; template <class Epi, int AI>
; __device__ __forceinline__ void skinny_item(LAS unsigned char* lds, const Gemm g, const Epi& E, const Unit u, int wr, int wc, int wave, int lane) {
;     ...
; #pragma unroll 1
;     for (int k = kbeg; k < kend; k += 128) {
;         SK_LOAD(a0, b0, k);
;         SK_LOAD(a1, b1, k + 64);
;         SK_MMA(a0, b0);
;         SK_MMA(a1, b1);
;     }
	v_mfma_f32_16x16x32_bf16 v[24:27], v[194:197], v[104:107], v[24:27]
	v_mfma_f32_16x16x32_bf16 v[20:23], v[194:197], v[100:103], v[20:23]
	global_load_dwordx4 v[100:103], v[192:193], off offset:192
	v_mfma_f32_16x16x32_bf16 v[8:11], v[194:197], v[140:143], v[8:11]
	v_mfma_f32_16x16x32_bf16 v[12:15], v[194:197], v[148:151], v[12:15]
	v_mfma_f32_16x16x32_bf16 v[32:35], v[160:163], v[152:155], v[32:35]
	v_mfma_f32_16x16x32_bf16 v[28:31], v[176:179], v[164:167], v[28:31]
	s_waitcnt vmcnt(16)
	v_mfma_f32_16x16x32_bf16 v[24:27], v[198:201], v[164:167], v[24:27]
	v_mfma_f32_16x16x32_bf16 v[16:19], v[176:179], v[136:139], v[16:19]
	v_mfma_f32_16x16x32_bf16 v[20:23], v[198:201], v[136:139], v[20:23]
	v_mfma_f32_16x16x32_bf16 v[4:7], v[176:179], v[144:147], v[4:7]
	v_mfma_f32_16x16x32_bf16 v[8:11], v[198:201], v[144:147], v[8:11]
	v_mfma_f32_16x16x32_bf16 v[0:3], v[176:179], v[152:155], v[0:3]
	v_mfma_f32_16x16x32_bf16 v[12:15], v[198:201], v[152:155], v[12:15]
	s_waitcnt vmcnt(13)
	v_mfma_f32_16x16x32_bf16 v[56:59], v[210:213], v[202:205], v[56:59]
	s_waitcnt vmcnt(11)
	v_mfma_f32_16x16x32_bf16 v[52:55], v[210:213], v[218:221], v[52:55]
	s_waitcnt vmcnt(9)
	v_mfma_f32_16x16x32_bf16 v[44:47], v[210:213], v[226:229], v[44:47]
	s_waitcnt vmcnt(7)
	v_mfma_f32_16x16x32_bf16 v[36:39], v[210:213], v[234:237], v[36:39]
	s_waitcnt vmcnt(5)
	v_mfma_f32_16x16x32_bf16 v[60:63], v[244:247], v[202:205], v[60:63]
	v_mfma_f32_16x16x32_bf16 v[48:51], v[244:247], v[218:221], v[48:51]
	v_mfma_f32_16x16x32_bf16 v[40:43], v[244:247], v[226:229], v[40:43]
	v_mfma_f32_16x16x32_bf16 v[32:35], v[244:247], v[234:237], v[32:35]
	s_waitcnt vmcnt(3)
	v_mfma_f32_16x16x32_bf16 v[28:31], v[156:159], v[202:205], v[28:31]
	s_waitcnt vmcnt(1)
	v_mfma_f32_16x16x32_bf16 v[24:27], v[96:99], v[202:205], v[24:27]
	v_mfma_f32_16x16x32_bf16 v[16:19], v[156:159], v[218:221], v[16:19]
	v_mfma_f32_16x16x32_bf16 v[20:23], v[96:99], v[218:221], v[20:23]
	v_mfma_f32_16x16x32_bf16 v[4:7], v[156:159], v[226:229], v[4:7]
	v_mfma_f32_16x16x32_bf16 v[8:11], v[96:99], v[226:229], v[8:11]
	v_mfma_f32_16x16x32_bf16 v[0:3], v[156:159], v[234:237], v[0:3]
	v_mfma_f32_16x16x32_bf16 v[12:15], v[96:99], v[234:237], v[12:15]
	v_mfma_f32_16x16x32_bf16 v[56:59], v[214:217], v[206:209], v[56:59]
	v_mfma_f32_16x16x32_bf16 v[60:63], v[248:251], v[206:209], v[60:63]
	v_mfma_f32_16x16x32_bf16 v[52:55], v[214:217], v[222:225], v[52:55]
	v_mfma_f32_16x16x32_bf16 v[48:51], v[248:251], v[222:225], v[48:51]
	v_mfma_f32_16x16x32_bf16 v[44:47], v[214:217], v[230:233], v[44:47]
	v_mfma_f32_16x16x32_bf16 v[40:43], v[248:251], v[230:233], v[40:43]
	v_mfma_f32_16x16x32_bf16 v[36:39], v[214:217], v[240:243], v[36:39]
	v_mfma_f32_16x16x32_bf16 v[32:35], v[248:251], v[240:243], v[32:35]
	v_mfma_f32_16x16x32_bf16 v[28:31], v[172:175], v[206:209], v[28:31]
	s_waitcnt vmcnt(0)
	v_mfma_f32_16x16x32_bf16 v[24:27], v[100:103], v[206:209], v[24:27]
	v_mfma_f32_16x16x32_bf16 v[16:19], v[172:175], v[222:225], v[16:19]
	v_mfma_f32_16x16x32_bf16 v[20:23], v[100:103], v[222:225], v[20:23]
	v_mfma_f32_16x16x32_bf16 v[4:7], v[172:175], v[230:233], v[4:7]
	v_mfma_f32_16x16x32_bf16 v[8:11], v[100:103], v[230:233], v[8:11]
	v_mfma_f32_16x16x32_bf16 v[0:3], v[172:175], v[240:243], v[0:3]
	v_mfma_f32_16x16x32_bf16 v[12:15], v[100:103], v[240:243], v[12:15]
	s_cbranch_scc1 .LBB0_1411
	s_andn2_b64 vcc, exec, s[84:85]
	s_cbranch_vccnz .LBB0_1414

; #define SK_MMA(A_, B_) do { _Pragma("unroll") for (int kk = 0; kk < 2; ++kk) _Pragma("unroll") for (int bj = 0; bj < 2; ++bj) _Pragma("unroll") for (int m = 0; m < 4; ++m) _Pragma("unroll") for (int n = 0; n < 2; ++n) \
;         acc[AI][bj][m][n] = __builtin_amdgcn_mfma_f32_16x16x32_bf16(B_[kk][bj][n], A_[kk][m], acc[AI][bj][m][n], 0, 0, 0); } while (0)
; template <class Epi, int AI>
; __device__ __forceinline__ void skinny_item(LAS unsigned char* lds, const Gemm g, const Epi& E, const Unit u, int wr, int wc, int wave, int lane) {
;     ...
; #pragma unroll 1
;     for (int k = kbeg; k < kend; k += 128) {
;         SK_LOAD(a0, b0, k);
;         SK_LOAD(a1, b1, k + 64);
;         SK_MMA(a0, b0);
;         SK_MMA(a1, b1);
;     }
.LBB0_1450:
	v_lshl_add_u64 v[104:105], v[92:93], 0, s[6:7]
	v_add_co_u32_e32 v186, vcc, s51, v104
	v_lshl_add_u64 v[106:107], v[66:67], 0, s[6:7]
	s_nop 1
	v_addc_co_u32_e32 v187, vcc, 0, v105, vcc
	v_lshl_add_u64 v[180:181], v[90:91], 0, s[6:7]
	v_add_co_u32_e32 v188, vcc, s51, v106
	v_lshl_add_u64 v[130:131], v[94:95], 0, s[6:7]
	v_lshl_add_u64 v[182:183], v[68:69], 0, s[6:7]
	v_lshl_add_u64 v[184:185], v[88:89], 0, s[6:7]
	v_addc_co_u32_e32 v189, vcc, 0, v107, vcc
	v_lshl_add_u64 v[164:165], v[70:71], 0, s[6:7]
	v_add_co_u32_e32 v190, vcc, s51, v164
	v_lshl_add_u64 v[168:169], v[64:65], 0, s[6:7]
	s_nop 1
	v_addc_co_u32_e32 v191, vcc, 0, v165, vcc
	v_add_co_u32_e32 v192, vcc, s51, v168
	s_nop 1
	v_addc_co_u32_e32 v193, vcc, 0, v169, vcc
	s_addk_i32 s8, 0x80
	s_add_u32 s6, s6, 0x100
	s_addc_u32 s7, s7, 0
	s_cmp_lt_i32 s8, s36
	global_load_dwordx4 v[104:107], v[130:131], off
	global_load_dwordx4 v[164:167], v[130:131], off offset:64
	global_load_dwordx4 v[168:171], v[186:187], off
	global_load_dwordx4 v[96:99], v[186:187], off offset:64
	global_load_dwordx4 v[100:103], v[180:181], off
	global_load_dwordx4 v[136:139], v[180:181], off offset:64
	global_load_dwordx4 v[140:143], v[182:183], off
	global_load_dwordx4 v[144:147], v[182:183], off offset:64
	global_load_dwordx4 v[148:151], v[184:185], off
	global_load_dwordx4 v[152:155], v[184:185], off offset:64
	global_load_dwordx4 v[156:159], v[188:189], off
	global_load_dwordx4 v[160:163], v[188:189], off offset:64
	global_load_dwordx4 v[172:175], v[190:191], off
	global_load_dwordx4 v[176:179], v[190:191], off offset:64
	global_load_dwordx4 v[194:197], v[192:193], off
	global_load_dwordx4 v[198:201], v[192:193], off offset:64
	global_load_dwordx4 v[202:205], v[130:131], off offset:128
	global_load_dwordx4 v[206:209], v[130:131], off offset:192
	global_load_dwordx4 v[210:213], v[186:187], off offset:128
	global_load_dwordx4 v[214:217], v[186:187], off offset:192
	global_load_dwordx4 v[218:221], v[180:181], off offset:128
	global_load_dwordx4 v[222:225], v[180:181], off offset:192
	global_load_dwordx4 v[226:229], v[182:183], off offset:128
	global_load_dwordx4 v[230:233], v[182:183], off offset:192
	global_load_dwordx4 v[234:237], v[184:185], off offset:128
	global_load_dwordx4 v[240:243], v[184:185], off offset:192
	global_load_dwordx4 v[244:247], v[188:189], off offset:128
	global_load_dwordx4 v[248:251], v[188:189], off offset:192
	s_waitcnt vmcnt(25)
	v_mfma_f32_16x16x32_bf16 v[56:59], v[168:171], v[104:107], v[56:59]
	s_waitcnt vmcnt(23)
	v_mfma_f32_16x16x32_bf16 v[52:55], v[168:171], v[100:103], v[52:55]
	s_waitcnt vmcnt(21)
	v_mfma_f32_16x16x32_bf16 v[44:47], v[168:171], v[140:143], v[44:47]
	s_waitcnt vmcnt(19)
	v_mfma_f32_16x16x32_bf16 v[36:39], v[168:171], v[148:151], v[36:39]
	s_waitcnt vmcnt(17)
	v_mfma_f32_16x16x32_bf16 v[60:63], v[156:159], v[104:107], v[60:63]
	v_mfma_f32_16x16x32_bf16 v[48:51], v[156:159], v[100:103], v[48:51]
	v_mfma_f32_16x16x32_bf16 v[40:43], v[156:159], v[140:143], v[40:43]
	v_mfma_f32_16x16x32_bf16 v[32:35], v[156:159], v[148:151], v[32:35]
	global_load_dwordx4 v[156:159], v[190:191], off offset:128
	s_waitcnt vmcnt(16)
	v_mfma_f32_16x16x32_bf16 v[28:31], v[172:175], v[104:107], v[28:31]
	v_mfma_f32_16x16x32_bf16 v[16:19], v[172:175], v[100:103], v[16:19]
	v_mfma_f32_16x16x32_bf16 v[4:7], v[172:175], v[140:143], v[4:7]
	v_mfma_f32_16x16x32_bf16 v[0:3], v[172:175], v[148:151], v[0:3]
	global_load_dwordx4 v[172:175], v[190:191], off offset:192
	v_mfma_f32_16x16x32_bf16 v[56:59], v[96:99], v[164:167], v[56:59]
	v_mfma_f32_16x16x32_bf16 v[60:63], v[160:163], v[164:167], v[60:63]
	v_mfma_f32_16x16x32_bf16 v[52:55], v[96:99], v[136:139], v[52:55]
	v_mfma_f32_16x16x32_bf16 v[48:51], v[160:163], v[136:139], v[48:51]
	v_mfma_f32_16x16x32_bf16 v[44:47], v[96:99], v[144:147], v[44:47]
	v_mfma_f32_16x16x32_bf16 v[40:43], v[160:163], v[144:147], v[40:43]
	v_mfma_f32_16x16x32_bf16 v[36:39], v[96:99], v[152:155], v[36:39]
	global_load_dwordx4 v[96:99], v[192:193], off offset:128
	s_waitcnt vmcnt(16)
; #define SK_MMA(A_, B_) do { _Pragma("unroll") for (int kk = 0; kk < 2; ++kk) _Pragma("unroll") for (int bj = 0; bj < 2; ++bj) _Pragma("unroll") for (int m = 0; m < 4; ++m) _Pragma("unroll") for (int n = 0; n < 2; ++n) \
;         acc[AI][bj][m][n] = __builtin_amdgcn_mfma_f32_16x16x32_bf16(B_[kk][bj][n], A_[kk][m], acc[AI][bj][m][n], 0, 0, 0); } while (0)
; template <class Epi, int AI>
; __device__ __forceinline__ void skinny_item(LAS unsigned char* lds, const Gemm g, const Epi& E, const Unit u, int wr, int wc, int wave, int lane) {
;     ...
; #pragma unroll 1
;     for (int k = kbeg; k < kend; k += 128) {
;         SK_LOAD(a0, b0, k);
;         SK_LOAD(a1, b1, k + 64);
;         SK_MMA(a0, b0);
;         SK_MMA(a1, b1);
;     }
	v_mfma_f32_16x16x32_bf16 v[24:27], v[194:197], v[104:107], v[24:27]
	v_mfma_f32_16x16x32_bf16 v[20:23], v[194:197], v[100:103], v[20:23]
	global_load_dwordx4 v[100:103], v[192:193], off offset:192
	v_mfma_f32_16x16x32_bf16 v[8:11], v[194:197], v[140:143], v[8:11]
	v_mfma_f32_16x16x32_bf16 v[12:15], v[194:197], v[148:151], v[12:15]
	v_mfma_f32_16x16x32_bf16 v[32:35], v[160:163], v[152:155], v[32:35]
	v_mfma_f32_16x16x32_bf16 v[28:31], v[176:179], v[164:167], v[28:31]
	s_waitcnt vmcnt(16)
	v_mfma_f32_16x16x32_bf16 v[24:27], v[198:201], v[164:167], v[24:27]
	v_mfma_f32_16x16x32_bf16 v[16:19], v[176:179], v[136:139], v[16:19]
	v_mfma_f32_16x16x32_bf16 v[20:23], v[198:201], v[136:139], v[20:23]
	v_mfma_f32_16x16x32_bf16 v[4:7], v[176:179], v[144:147], v[4:7]
	v_mfma_f32_16x16x32_bf16 v[8:11], v[198:201], v[144:147], v[8:11]
	v_mfma_f32_16x16x32_bf16 v[0:3], v[176:179], v[152:155], v[0:3]
	v_mfma_f32_16x16x32_bf16 v[12:15], v[198:201], v[152:155], v[12:15]
	s_waitcnt vmcnt(13)
	v_mfma_f32_16x16x32_bf16 v[56:59], v[210:213], v[202:205], v[56:59]
	s_waitcnt vmcnt(11)
	v_mfma_f32_16x16x32_bf16 v[52:55], v[210:213], v[218:221], v[52:55]
	s_waitcnt vmcnt(9)
	v_mfma_f32_16x16x32_bf16 v[44:47], v[210:213], v[226:229], v[44:47]
	s_waitcnt vmcnt(7)
	v_mfma_f32_16x16x32_bf16 v[36:39], v[210:213], v[234:237], v[36:39]
	s_waitcnt vmcnt(5)
	v_mfma_f32_16x16x32_bf16 v[60:63], v[244:247], v[202:205], v[60:63]
	v_mfma_f32_16x16x32_bf16 v[48:51], v[244:247], v[218:221], v[48:51]
	v_mfma_f32_16x16x32_bf16 v[40:43], v[244:247], v[226:229], v[40:43]
	v_mfma_f32_16x16x32_bf16 v[32:35], v[244:247], v[234:237], v[32:35]
	s_waitcnt vmcnt(3)
	v_mfma_f32_16x16x32_bf16 v[28:31], v[156:159], v[202:205], v[28:31]
	s_waitcnt vmcnt(1)
	v_mfma_f32_16x16x32_bf16 v[24:27], v[96:99], v[202:205], v[24:27]
	v_mfma_f32_16x16x32_bf16 v[16:19], v[156:159], v[218:221], v[16:19]
	v_mfma_f32_16x16x32_bf16 v[20:23], v[96:99], v[218:221], v[20:23]
	v_mfma_f32_16x16x32_bf16 v[4:7], v[156:159], v[226:229], v[4:7]
	v_mfma_f32_16x16x32_bf16 v[8:11], v[96:99], v[226:229], v[8:11]
	v_mfma_f32_16x16x32_bf16 v[0:3], v[156:159], v[234:237], v[0:3]
	v_mfma_f32_16x16x32_bf16 v[12:15], v[96:99], v[234:237], v[12:15]
	v_mfma_f32_16x16x32_bf16 v[56:59], v[214:217], v[206:209], v[56:59]
	v_mfma_f32_16x16x32_bf16 v[60:63], v[248:251], v[206:209], v[60:63]
	v_mfma_f32_16x16x32_bf16 v[52:55], v[214:217], v[222:225], v[52:55]
	v_mfma_f32_16x16x32_bf16 v[48:51], v[248:251], v[222:225], v[48:51]
	v_mfma_f32_16x16x32_bf16 v[44:47], v[214:217], v[230:233], v[44:47]
	v_mfma_f32_16x16x32_bf16 v[40:43], v[248:251], v[230:233], v[40:43]
	v_mfma_f32_16x16x32_bf16 v[36:39], v[214:217], v[240:243], v[36:39]
	v_mfma_f32_16x16x32_bf16 v[32:35], v[248:251], v[240:243], v[32:35]
	v_mfma_f32_16x16x32_bf16 v[28:31], v[172:175], v[206:209], v[28:31]
	s_waitcnt vmcnt(0)
	v_mfma_f32_16x16x32_bf16 v[24:27], v[100:103], v[206:209], v[24:27]
	v_mfma_f32_16x16x32_bf16 v[16:19], v[172:175], v[222:225], v[16:19]
	v_mfma_f32_16x16x32_bf16 v[20:23], v[100:103], v[222:225], v[20:23]
	v_mfma_f32_16x16x32_bf16 v[4:7], v[172:175], v[230:233], v[4:7]
	v_mfma_f32_16x16x32_bf16 v[8:11], v[100:103], v[230:233], v[8:11]
	v_mfma_f32_16x16x32_bf16 v[0:3], v[172:175], v[240:243], v[0:3]
	v_mfma_f32_16x16x32_bf16 v[12:15], v[100:103], v[240:243], v[12:15]
	s_cbranch_scc1 .LBB0_1450
	s_andn2_b64 vcc, exec, s[84:85]
	s_cbranch_vccnz .LBB0_1453
